# v13 + attention Q and gate loads with default cache policy instead of nt
# speedup vs baseline: 1.0158x; 1.0100x over previous
.LBB0_735:
	s_or_b64 exec, exec, s[10:11]
	s_ashr_i32 s4, s39, 31
	v_lshrrev_b32_e32 v81, 3, v194
	v_or_b32_e32 v78, s39, v81
	v_mov_b32_e32 v79, s4
	v_and_b32_e32 v82, 56, v192
	v_lshlrev_b64 v[64:65], 12, v[78:79]
	v_add_u32_e32 v80, s48, v176
	v_lshl_add_u64 v[64:65], s[88:89], 0, v[64:65]
	v_lshlrev_b32_e32 v176, 1, v82
	s_waitcnt lgkmcnt(0)
	v_lshl_add_u64 v[64:65], v[64:65], 0, v[176:177]
	v_lshl_add_u32 v156, v78, 12, v176
	global_load_dwordx4 v[70:73], v[64:65], off
	v_add_u32_e32 v157, 0x8000, v156
	global_load_dwordx4 v[128:131], v157, s[88:89]
	v_add_u32_e32 v157, 0x10000, v156
	global_load_dwordx4 v[132:135], v157, s[88:89]
	v_add_u32_e32 v157, 0x18000, v156
	global_load_dwordx4 v[136:139], v157, s[88:89]
	global_load_dwordx4 v[140:143], v156, s[88:89] offset:128
	v_add_u32_e32 v157, 0x8000, v156
	global_load_dwordx4 v[144:147], v157, s[88:89] offset:128
	v_add_u32_e32 v157, 0x10000, v156
	global_load_dwordx4 v[148:151], v157, s[88:89] offset:128
	v_add_u32_e32 v157, 0x18000, v156
	global_load_dwordx4 v[152:155], v157, s[88:89] offset:128
	ds_read_b128 v[66:69], v80
	ds_read_b128 v[74:77], v80 offset:32
	s_lshl_b32 s4, s42, 13
	s_add_i32 s4, s4, 0
	v_lshlrev_b32_e32 v78, 10, v191
	s_waitcnt lgkmcnt(1)
	v_rcp_f32_e32 v83, v66
	v_rcp_f32_e32 v84, v67
	v_rcp_f32_e32 v85, v68
	v_rcp_f32_e32 v86, v69
	s_waitcnt lgkmcnt(0)
	v_rcp_f32_e32 v87, v74
	ds_read_b128 v[66:69], v80 offset:64
	v_rcp_f32_e32 v88, v75
	v_rcp_f32_e32 v89, v76
	v_rcp_f32_e32 v90, v77
	ds_read_b128 v[74:77], v80 offset:96
	v_lshlrev_b32_e32 v80, 2, v190
	v_add3_u32 v80, s4, v78, v80
	v_mul_f32_e32 v32, v32, v83
	v_mul_f32_e32 v48, v48, v83
	ds_write2_b32 v80, v32, v48 offset1:32
	v_mul_f32_e32 v32, v33, v84
	v_mul_f32_e32 v33, v49, v84
	ds_write2_b32 v80, v32, v33 offset0:64 offset1:96
	v_mul_f32_e32 v32, v34, v85
	v_mul_f32_e32 v33, v50, v85
	ds_write2_b32 v80, v32, v33 offset0:128 offset1:160
	v_mul_f32_e32 v32, v35, v86
	v_mul_f32_e32 v33, v51, v86
	s_waitcnt lgkmcnt(4)
	v_rcp_f32_e32 v66, v66
	ds_write2_b32 v80, v32, v33 offset0:192 offset1:224
	v_mul_f32_e32 v32, v36, v87
	v_mul_f32_e32 v33, v52, v87
	v_add_u32_e32 v92, 0x800, v80
	v_rcp_f32_e32 v67, v67
	ds_write2_b32 v92, v32, v33 offset1:32
	v_mul_f32_e32 v32, v37, v88
	v_mul_f32_e32 v33, v53, v88
	v_rcp_f32_e32 v68, v68
	ds_write2_b32 v92, v32, v33 offset0:64 offset1:96
	v_mul_f32_e32 v32, v38, v89
	v_mul_f32_e32 v33, v54, v89
	v_rcp_f32_e32 v69, v69
	ds_write2_b32 v92, v32, v33 offset0:128 offset1:160
	v_mul_f32_e32 v32, v39, v90
	v_mul_f32_e32 v33, v55, v90
	s_waitcnt lgkmcnt(7)
	v_rcp_f32_e32 v74, v74
	ds_write2_b32 v92, v32, v33 offset0:192 offset1:224
	v_mul_f32_e32 v32, v40, v66
	v_mul_f32_e32 v33, v56, v66
	v_add_u32_e32 v54, 0x1000, v80
	v_rcp_f32_e32 v75, v75
	ds_write2_b32 v54, v32, v33 offset1:32
	v_mul_f32_e32 v32, v41, v67
	v_mul_f32_e32 v33, v57, v67
	v_rcp_f32_e32 v76, v76
	ds_write2_b32 v54, v32, v33 offset0:64 offset1:96
	v_mul_f32_e32 v32, v42, v68
	v_mul_f32_e32 v33, v58, v68
	ds_write2_b32 v54, v32, v33 offset0:128 offset1:160
	v_mul_f32_e32 v32, v43, v69
	v_mul_f32_e32 v33, v59, v69
	ds_write2_b32 v54, v32, v33 offset0:192 offset1:224
	v_mul_f32_e32 v32, v44, v74
	v_mul_f32_e32 v33, v60, v74
	v_add_u32_e32 v55, 0x1800, v80
	v_lshl_add_u32 v82, v82, 2, s4
	ds_write2_b32 v55, v32, v33 offset1:32
	v_mul_f32_e32 v32, v45, v75
	v_mul_f32_e32 v33, v61, v75
	v_lshl_add_u32 v91, v81, 8, v82
	ds_write2_b32 v55, v32, v33 offset0:64 offset1:96
	v_mul_f32_e32 v32, v46, v76
	v_mul_f32_e32 v33, v62, v76
	v_rcp_f32_e32 v77, v77
	ds_write2_b32 v55, v32, v33 offset0:128 offset1:160
	ds_read_b128 v[32:35], v91
	v_or_b32_e32 v44, 8, v81
	v_mul_f32_e32 v36, v47, v77
	v_mul_f32_e32 v37, v63, v77
	s_waitcnt vmcnt(7)
	v_lshlrev_b32_e32 v40, 16, v70
	ds_write2_b32 v55, v36, v37 offset0:192 offset1:224
	ds_read_b128 v[36:39], v91 offset:16
	s_waitcnt lgkmcnt(2)
	v_mul_f32_e32 v32, v32, v40
	v_and_b32_e32 v40, 0xffff0000, v70
	v_mul_f32_e32 v33, v33, v40
	v_cvt_pk_bf16_f32 v40, v32, v33
	v_lshlrev_b32_e32 v32, 16, v71
	v_and_b32_e32 v33, 0xffff0000, v71
	v_mul_f32_e32 v32, v34, v32
	v_mul_f32_e32 v33, v35, v33
	v_cvt_pk_bf16_f32 v41, v32, v33
	v_lshlrev_b32_e32 v32, 16, v72
	v_and_b32_e32 v33, 0xffff0000, v72
	s_waitcnt lgkmcnt(0)
	v_mul_f32_e32 v32, v36, v32
	v_mul_f32_e32 v33, v37, v33
	v_cvt_pk_bf16_f32 v42, v32, v33
	v_lshlrev_b32_e32 v32, 16, v73
	v_and_b32_e32 v33, 0xffff0000, v73
	v_mul_f32_e32 v32, v38, v32
	v_mul_f32_e32 v33, v39, v33
	v_or_b32_e32 v78, s39, v44
	v_cvt_pk_bf16_f32 v43, v32, v33
	v_lshlrev_b64 v[32:33], 12, v[78:79]
	v_lshl_add_u64 v[32:33], s[88:89], 0, v[32:33]
	v_lshl_add_u64 v[34:35], v[32:33], 0, v[176:177]
	v_lshl_add_u32 v56, v44, 8, v82
	ds_read_b128 v[44:47], v56
	ds_read_b128 v[48:51], v56 offset:16
	v_or_b32_e32 v52, 16, v81
	v_or_b32_e32 v78, s39, v52
	v_lshlrev_b64 v[32:33], 12, v[78:79]
	v_lshl_add_u64 v[32:33], s[88:89], 0, v[32:33]
	global_store_dwordx4 v[64:65], v[40:43], off
	v_lshl_add_u64 v[32:33], v[32:33], 0, v[176:177]
	v_lshl_add_u32 v58, v52, 8, v82
	v_or_b32_e32 v57, 24, v81
	v_or_b32_e32 v78, s39, v57
	v_lshl_add_u32 v57, v57, 8, v82
	v_mul_f32_e32 v0, v0, v83
	v_mul_f32_e32 v16, v16, v83
	v_mul_f32_e32 v1, v1, v84
	v_mul_f32_e32 v17, v17, v84
	v_mul_f32_e32 v2, v2, v85
	v_mul_f32_e32 v18, v18, v85
	v_mul_f32_e32 v3, v3, v86
	v_mul_f32_e32 v19, v19, v86
	v_mul_f32_e32 v4, v4, v87
	v_mul_f32_e32 v20, v20, v87
	v_mul_f32_e32 v5, v5, v88
	v_mul_f32_e32 v21, v21, v88
	v_mul_f32_e32 v6, v6, v89
	v_mul_f32_e32 v22, v22, v89
	v_mul_f32_e32 v7, v7, v90
	v_mul_f32_e32 v23, v23, v90
	v_mul_f32_e32 v8, v8, v66
	v_mul_f32_e32 v24, v24, v66
	v_mul_f32_e32 v9, v9, v67
	v_mul_f32_e32 v25, v25, v67
	v_mul_f32_e32 v10, v10, v68
	v_mul_f32_e32 v26, v26, v68
	v_mul_f32_e32 v11, v11, v69
	v_mul_f32_e32 v27, v27, v69
	v_mul_f32_e32 v12, v12, v74
	v_mul_f32_e32 v28, v28, v74
	v_mul_f32_e32 v13, v13, v75
	v_mul_f32_e32 v29, v29, v75
	v_mul_f32_e32 v14, v14, v76
	v_mul_f32_e32 v30, v30, v76
	v_mul_f32_e32 v15, v15, v77
	v_mul_f32_e32 v31, v31, v77
	s_add_i32 s41, s41, 1
	s_cmp_eq_u32 s41, 4
	s_waitcnt vmcnt(7)
	v_mov_b64_e32 v[36:37], v[128:129]
	v_mov_b64_e32 v[38:39], v[130:131]
	v_lshlrev_b32_e32 v40, 16, v36
	v_and_b32_e32 v36, 0xffff0000, v36
	v_lshlrev_b32_e32 v41, 16, v37
	v_lshlrev_b32_e32 v42, 16, v38
	v_and_b32_e32 v38, 0xffff0000, v38
	v_lshlrev_b32_e32 v43, 16, v39
	v_and_b32_e32 v39, 0xffff0000, v39
	v_and_b32_e32 v37, 0xffff0000, v37
	s_waitcnt lgkmcnt(1)
	v_mul_f32_e32 v40, v44, v40
	v_mul_f32_e32 v36, v45, v36
	v_mul_f32_e32 v41, v46, v41
	s_waitcnt lgkmcnt(0)
	v_mul_f32_e32 v42, v48, v42
	v_mul_f32_e32 v44, v49, v38
	v_mul_f32_e32 v43, v50, v43
	v_mul_f32_e32 v45, v51, v39
	v_mul_f32_e32 v37, v47, v37
	v_cvt_pk_bf16_f32 v38, v40, v36
	v_cvt_pk_bf16_f32 v39, v41, v37
	v_cvt_pk_bf16_f32 v40, v42, v44
	v_cvt_pk_bf16_f32 v41, v43, v45
	ds_read_b128 v[46:49], v58
	ds_read_b128 v[50:53], v58 offset:16
	v_lshlrev_b64 v[36:37], 12, v[78:79]
	v_lshl_add_u64 v[36:37], s[88:89], 0, v[36:37]
	global_store_dwordx4 v[34:35], v[38:41], off
	v_lshl_add_u64 v[36:37], v[36:37], 0, v[176:177]
	s_waitcnt vmcnt(7)
	v_mov_b64_e32 v[42:43], v[132:133]
	v_mov_b64_e32 v[44:45], v[134:135]
	v_lshlrev_b32_e32 v38, 16, v42
	v_and_b32_e32 v39, 0xffff0000, v42
	v_lshlrev_b32_e32 v40, 16, v43
	v_and_b32_e32 v41, 0xffff0000, v43
	v_lshlrev_b32_e32 v42, 16, v44
	v_and_b32_e32 v43, 0xffff0000, v44
	v_lshlrev_b32_e32 v44, 16, v45
	v_and_b32_e32 v45, 0xffff0000, v45
	s_waitcnt lgkmcnt(1)
	v_mul_f32_e32 v38, v46, v38
	v_mul_f32_e32 v39, v47, v39
	v_mul_f32_e32 v40, v48, v40
	v_mul_f32_e32 v41, v49, v41
	s_waitcnt lgkmcnt(0)
	v_mul_f32_e32 v42, v50, v42
	v_mul_f32_e32 v43, v51, v43
	v_mul_f32_e32 v44, v52, v44
	v_mul_f32_e32 v45, v53, v45
	v_cvt_pk_bf16_f32 v38, v38, v39
	v_cvt_pk_bf16_f32 v39, v40, v41
	v_cvt_pk_bf16_f32 v40, v42, v43
	v_cvt_pk_bf16_f32 v41, v44, v45
	ds_read_b128 v[46:49], v57
	ds_read_b128 v[50:53], v57 offset:16
	global_store_dwordx4 v[32:33], v[38:41], off
	s_waitcnt vmcnt(7)
	v_mov_b64_e32 v[42:43], v[136:137]
	v_mov_b64_e32 v[44:45], v[138:139]
	s_nop 0
	v_lshlrev_b32_e32 v38, 16, v42
	v_and_b32_e32 v39, 0xffff0000, v42
	v_lshlrev_b32_e32 v40, 16, v43
	v_and_b32_e32 v41, 0xffff0000, v43
	v_lshlrev_b32_e32 v42, 16, v44
	v_and_b32_e32 v43, 0xffff0000, v44
	v_lshlrev_b32_e32 v44, 16, v45
	v_and_b32_e32 v45, 0xffff0000, v45
	s_waitcnt lgkmcnt(1)
	v_mul_f32_e32 v38, v46, v38
	v_mul_f32_e32 v39, v47, v39
	v_mul_f32_e32 v40, v48, v40
	v_mul_f32_e32 v41, v49, v41
	s_waitcnt lgkmcnt(0)
	v_mul_f32_e32 v42, v50, v42
	v_mul_f32_e32 v43, v51, v43
	v_mul_f32_e32 v44, v52, v44
	v_mul_f32_e32 v45, v53, v45
	v_cvt_pk_bf16_f32 v38, v38, v39
	v_cvt_pk_bf16_f32 v39, v40, v41
	v_cvt_pk_bf16_f32 v40, v42, v43
	v_cvt_pk_bf16_f32 v41, v44, v45
	ds_write2_b32 v80, v0, v16 offset1:32
	ds_write2_b32 v80, v1, v17 offset0:64 offset1:96
	ds_write2_b32 v80, v2, v18 offset0:128 offset1:160
	ds_write2_b32 v80, v3, v19 offset0:192 offset1:224
	ds_write2_b32 v92, v4, v20 offset1:32
	ds_write2_b32 v92, v5, v21 offset0:64 offset1:96
	ds_write2_b32 v92, v6, v22 offset0:128 offset1:160
	ds_write2_b32 v92, v7, v23 offset0:192 offset1:224
	ds_write2_b32 v54, v8, v24 offset1:32
	ds_write2_b32 v54, v9, v25 offset0:64 offset1:96
	ds_write2_b32 v54, v10, v26 offset0:128 offset1:160
	ds_write2_b32 v54, v11, v27 offset0:192 offset1:224
	ds_write2_b32 v55, v12, v28 offset1:32
	ds_write2_b32 v55, v13, v29 offset0:64 offset1:96
	ds_write2_b32 v55, v14, v30 offset0:128 offset1:160
	ds_write2_b32 v55, v15, v31 offset0:192 offset1:224
	global_store_dwordx4 v[36:37], v[38:41], off
	ds_read_b128 v[0:3], v91
	ds_read_b128 v[4:7], v91 offset:16
	s_waitcnt vmcnt(7)
	v_mov_b64_e32 v[42:43], v[140:141]
	v_mov_b64_e32 v[44:45], v[142:143]
	v_lshlrev_b32_e32 v8, 16, v42
	v_and_b32_e32 v9, 0xffff0000, v42
	v_lshlrev_b32_e32 v10, 16, v43
	v_and_b32_e32 v11, 0xffff0000, v43
	v_lshlrev_b32_e32 v12, 16, v44
	v_and_b32_e32 v13, 0xffff0000, v44
	v_lshlrev_b32_e32 v14, 16, v45
	v_and_b32_e32 v15, 0xffff0000, v45
	s_waitcnt lgkmcnt(1)
	v_mul_f32_e32 v0, v0, v8
	v_mul_f32_e32 v1, v1, v9
	v_mul_f32_e32 v2, v2, v10
	v_mul_f32_e32 v3, v3, v11
	s_waitcnt lgkmcnt(0)
	v_mul_f32_e32 v4, v4, v12
	v_mul_f32_e32 v5, v5, v13
	v_mul_f32_e32 v6, v6, v14
	v_mul_f32_e32 v7, v7, v15
	v_cvt_pk_bf16_f32 v0, v0, v1
	v_cvt_pk_bf16_f32 v1, v2, v3
	v_cvt_pk_bf16_f32 v2, v4, v5
	v_cvt_pk_bf16_f32 v3, v6, v7
	ds_read_b128 v[8:11], v56
	ds_read_b128 v[12:15], v56 offset:16
	global_store_dwordx4 v[64:65], v[0:3], off offset:128
	s_waitcnt vmcnt(7)
	v_mov_b64_e32 v[4:5], v[144:145]
	v_mov_b64_e32 v[6:7], v[146:147]
	s_nop 0
	v_lshlrev_b32_e32 v0, 16, v4
	v_and_b32_e32 v1, 0xffff0000, v4
	v_lshlrev_b32_e32 v2, 16, v5
	v_and_b32_e32 v3, 0xffff0000, v5
	v_lshlrev_b32_e32 v4, 16, v6
	v_and_b32_e32 v5, 0xffff0000, v6
	v_lshlrev_b32_e32 v6, 16, v7
	v_and_b32_e32 v7, 0xffff0000, v7
	s_waitcnt lgkmcnt(1)
	v_mul_f32_e32 v0, v8, v0
	v_mul_f32_e32 v1, v9, v1
	v_mul_f32_e32 v2, v10, v2
	v_mul_f32_e32 v3, v11, v3
	s_waitcnt lgkmcnt(0)
	v_mul_f32_e32 v4, v12, v4
	v_mul_f32_e32 v5, v13, v5
	v_mul_f32_e32 v6, v14, v6
	v_mul_f32_e32 v7, v15, v7
	v_cvt_pk_bf16_f32 v0, v0, v1
	v_cvt_pk_bf16_f32 v1, v2, v3
	v_cvt_pk_bf16_f32 v2, v4, v5
	v_cvt_pk_bf16_f32 v3, v6, v7
	ds_read_b128 v[8:11], v58
	ds_read_b128 v[12:15], v58 offset:16
	global_store_dwordx4 v[34:35], v[0:3], off offset:128
	s_waitcnt vmcnt(7)
	v_mov_b64_e32 v[4:5], v[148:149]
	v_mov_b64_e32 v[6:7], v[150:151]
	s_nop 0
	v_lshlrev_b32_e32 v0, 16, v4
	v_and_b32_e32 v1, 0xffff0000, v4
	v_lshlrev_b32_e32 v2, 16, v5
	v_and_b32_e32 v3, 0xffff0000, v5
	v_lshlrev_b32_e32 v4, 16, v6
	v_and_b32_e32 v5, 0xffff0000, v6
	v_lshlrev_b32_e32 v6, 16, v7
	v_and_b32_e32 v7, 0xffff0000, v7
	s_waitcnt lgkmcnt(1)
	v_mul_f32_e32 v0, v8, v0
	v_mul_f32_e32 v1, v9, v1
	v_mul_f32_e32 v2, v10, v2
	v_mul_f32_e32 v3, v11, v3
	s_waitcnt lgkmcnt(0)
	v_mul_f32_e32 v4, v12, v4
	v_mul_f32_e32 v5, v13, v5
	v_mul_f32_e32 v6, v14, v6
	v_mul_f32_e32 v7, v15, v7
	v_cvt_pk_bf16_f32 v0, v0, v1
	v_cvt_pk_bf16_f32 v1, v2, v3
	v_cvt_pk_bf16_f32 v2, v4, v5
	v_cvt_pk_bf16_f32 v3, v6, v7
	ds_read_b128 v[8:11], v57
	ds_read_b128 v[12:15], v57 offset:16
	global_store_dwordx4 v[32:33], v[0:3], off offset:128
	s_waitcnt vmcnt(7)
	v_mov_b64_e32 v[4:5], v[152:153]
	v_mov_b64_e32 v[6:7], v[154:155]
	s_nop 0
	v_lshlrev_b32_e32 v0, 16, v4
	v_and_b32_e32 v1, 0xffff0000, v4
	v_lshlrev_b32_e32 v2, 16, v5
	v_and_b32_e32 v3, 0xffff0000, v5
	v_lshlrev_b32_e32 v4, 16, v6
	v_and_b32_e32 v5, 0xffff0000, v6
	v_lshlrev_b32_e32 v6, 16, v7
	v_and_b32_e32 v7, 0xffff0000, v7
	s_waitcnt lgkmcnt(1)
	v_mul_f32_e32 v0, v8, v0
	v_mul_f32_e32 v1, v9, v1
	v_mul_f32_e32 v2, v10, v2
	v_mul_f32_e32 v3, v11, v3
	s_waitcnt lgkmcnt(0)
	v_mul_f32_e32 v4, v12, v4
	v_mul_f32_e32 v5, v13, v5
	v_mul_f32_e32 v6, v14, v6
	v_mul_f32_e32 v7, v15, v7
	v_cvt_pk_bf16_f32 v0, v0, v1
	v_cvt_pk_bf16_f32 v1, v2, v3
	v_cvt_pk_bf16_f32 v2, v4, v5
	v_cvt_pk_bf16_f32 v3, v6, v7
	global_store_dwordx4 v[36:37], v[0:3], off offset:128
	s_waitcnt lgkmcnt(0)
	s_barrier
	s_cbranch_scc1 .LBB0_733

.LBB0_741:
	v_mov_b32_e32 v195, v193
	s_lshl_b32 s10, s4, 8
	v_readfirstlane_b32 s8, v195
	s_movk_i32 s4, 0xffc0
	s_and_b32 s11, s8, 0xffffffc0
	v_mov_b32_e32 v0, s8
	v_bfi_b32 v0, s4, v0, v195
	v_mul_hi_i32 v1, v0, s69
	v_lshrrev_b32_e32 v2, 31, v1
	v_ashrrev_i32_e32 v1, 2, v1
	s_lshl_b32 s9, s11, 2
	v_add_u32_e32 v1, v1, v2
	s_ashr_i32 s42, s8, 6
	s_add_i32 s48, s9, 0
	v_mad_u64_u32 v[2:3], s[8:9], v1, s1, v[0:1]
	v_lshrrev_b32_e32 v3, 1, v1
	v_bitop3_b32 v2, v2, v3, 7 bitop3:0x78
	v_mul_lo_u32 v1, v1, s47
	v_lshl_add_u32 v180, v2, 3, v1
	v_add_u32_e32 v2, 0x200, v0
	v_mul_hi_i32 v1, v2, s69
	v_lshrrev_b32_e32 v3, 31, v1
	v_ashrrev_i32_e32 v1, 2, v1
	v_add_u32_e32 v1, v1, v3
	v_mad_u64_u32 v[2:3], s[8:9], v1, s1, v[2:3]
	v_lshrrev_b32_e32 v3, 1, v1
	v_bitop3_b32 v2, v2, v3, 7 bitop3:0x78
	v_mul_lo_u32 v1, v1, s47
	v_lshl_add_u32 v182, v2, 3, v1
	v_add_u32_e32 v2, 0x400, v0
	v_mul_hi_i32 v1, v2, s69
	v_lshrrev_b32_e32 v3, 31, v1
	v_ashrrev_i32_e32 v1, 2, v1
	v_add_u32_e32 v1, v1, v3
	v_mad_u64_u32 v[2:3], s[8:9], v1, s1, v[2:3]
	s_lshl_b32 s39, s42, 5
	v_lshrrev_b32_e32 v3, 1, v1
	v_and_b32_e32 v190, 31, v195
	s_add_i32 s39, s39, s10
	v_bitop3_b32 v2, v2, v3, 7 bitop3:0x78
	v_mul_lo_u32 v1, v1, s47
	v_lshlrev_b32_e32 v192, 3, v195
	v_or_b32_e32 v40, s39, v190
	v_lshl_add_u32 v184, v2, 3, v1
	v_mov_b64_e32 v[2:3], s[80:81]
	v_and_b32_e32 v4, 24, v192
	s_movk_i32 s4, 0x60
	v_mad_i64_i32 v[2:3], s[8:9], v40, s35, v[2:3]
	v_and_or_b32 v0, v0, s4, v4
	s_ashr_i32 s4, s11, 4
	s_and_b32 s8, s4, 0x1fffff0
	s_lshr_b32 s4, s4, 1
	v_bfe_u32 v1, v195, 2, 2
	v_lshrrev_b32_e32 v194, 1, v195
	s_and_b32 s4, s4, 4
	v_and_or_b32 v1, v194, 8, v1
	s_or_b32 s4, s8, s4
	s_addk_i32 s11, 0x200
	v_or_b32_e32 v4, s4, v1
	s_ashr_i32 s4, s11, 4
	s_and_b32 s8, s4, 0x1fffff0
	s_lshr_b32 s4, s4, 1
	s_and_b32 s4, s4, 4
	s_add_i32 s48, s48, 0x1e000
	s_or_b32 s4, s8, s4
	s_lshl_b32 s51, s42, 10
	v_ashrrev_i32_e32 v181, 31, v180
	v_or_b32_e32 v1, s4, v1
	v_lshlrev_b64 v[100:101], 1, v[180:181]
	s_cmp_lg_u32 0, -1
	v_ashrrev_i32_e32 v183, 31, v182
	v_lshl_or_b32 v186, v4, 7, v0
	v_lshl_or_b32 v188, v1, 7, v0
	v_lshl_add_u64 v[0:1], s[82:83], 0, v[100:101]
	s_cselect_b32 s4, 0, 0
	v_lshlrev_b64 v[102:103], 1, v[182:183]
	v_ashrrev_i32_e32 v185, 31, v184
	s_add_i32 s49, s51, s4
	s_mov_b32 s8, m0
	s_mov_b32 m0, s49
	s_nop 0
	global_load_lds_dwordx4 v[0:1], off
	s_mov_b32 m0, s8
	v_lshl_add_u64 v[0:1], s[82:83], 0, v[102:103]
	v_lshlrev_b64 v[104:105], 1, v[184:185]
	v_ashrrev_i32_e32 v187, 31, v186
	s_add_i32 s8, s49, 0x2000
	s_mov_b32 s9, m0
	s_mov_b32 m0, s8
	s_nop 0
	global_load_lds_dwordx4 v[0:1], off
	s_mov_b32 m0, s9
	v_lshl_add_u64 v[0:1], s[82:83], 0, v[104:105]
	v_lshlrev_b64 v[106:107], 1, v[186:187]
	v_ashrrev_i32_e32 v189, 31, v188
	s_add_i32 s8, s49, 0x4000
	s_mov_b32 s9, m0
	s_mov_b32 m0, s8
	s_nop 0
	global_load_lds_dwordx4 v[0:1], off
	s_mov_b32 m0, s9
	v_lshl_add_u64 v[0:1], s[86:87], 0, v[106:107]
	s_add_i32 s11, s4, 0x12000
	v_lshlrev_b64 v[108:109], 1, v[188:189]
	s_add_i32 s51, s51, s11
	s_mov_b32 s8, m0
	s_mov_b32 m0, s51
	s_nop 0
	global_load_lds_dwordx4 v[0:1], off
	s_mov_b32 m0, s8
	v_lshl_add_u64 v[0:1], s[86:87], 0, v[108:109]
	s_add_i32 s8, s49, 0x14000
	s_mov_b32 s9, m0
	s_mov_b32 m0, s8
	s_nop 0
	global_load_lds_dwordx4 v[0:1], off
	s_mov_b32 m0, s9
	v_lshl_add_u64 v[0:1], s[94:95], 0, v[100:101]
	v_bfe_u32 v191, v195, 5, 1
	s_add_i32 s8, s49, 0x6000
	s_mov_b32 s9, m0
	s_mov_b32 m0, s8
	s_nop 0
	global_load_lds_dwordx4 v[0:1], off
	s_mov_b32 m0, s9
	v_lshl_add_u64 v[0:1], s[94:95], 0, v[102:103]
	s_add_i32 s8, s49, 0x8000
	s_mov_b32 s9, m0
	s_mov_b32 m0, s8
	s_nop 0
	global_load_lds_dwordx4 v[0:1], off
	s_mov_b32 m0, s9
	v_lshl_add_u64 v[0:1], s[94:95], 0, v[104:105]
	v_lshlrev_b32_e32 v176, 4, v191
	s_add_i32 s8, s49, 0xa000
	s_mov_b32 s9, m0
	s_mov_b32 m0, s8
	s_nop 0
	global_load_lds_dwordx4 v[0:1], off
	s_mov_b32 m0, s9
	v_lshl_add_u64 v[0:1], v[2:3], 0, v[176:177]
	global_load_dwordx4 v[2:5], v[0:1], off
	global_load_dwordx4 v[6:9], v[0:1], off offset:32
	global_load_dwordx4 v[10:13], v[0:1], off offset:64
	global_load_dwordx4 v[14:17], v[0:1], off offset:96
	global_load_dwordx4 v[18:21], v[0:1], off offset:128
	global_load_dwordx4 v[22:25], v[0:1], off offset:160
	v_and_b32_e32 v46, 32, v195
	v_ashrrev_i32_e32 v41, 31, v40
	v_lshlrev_b64 v[40:41], 7, v[40:41]
	v_or_b32_e32 v40, v40, v46
	v_lshl_add_u64 v[150:151], s[90:91], 0, v[40:41]
	v_lshl_add_u64 v[152:153], s[92:93], 0, v[40:41]
	s_mov_b32 s16, 0
	s_mov_b32 s30, s16
	s_mov_b32 s31, s16
	s_addk_i32 s10, 0x100
	s_ashr_i32 s52, s39, 6
	s_mov_b32 s17, s16
	s_mov_b32 s18, s16
	s_mov_b32 s19, s16
	s_mov_b32 s20, s16
	s_mov_b32 s21, s16
	s_mov_b32 s22, s16
	s_mov_b32 s23, s16
	s_mov_b32 s24, s16
	s_mov_b32 s25, s16
	s_mov_b32 s26, s16
	s_mov_b32 s27, s16
	s_mov_b32 s28, s16
	s_mov_b32 s29, s16
	s_lshr_b32 s56, s10, 6
	s_mov_b32 s62, 1
	s_mov_b32 s63, 4
	s_waitcnt vmcnt(5)
	v_lshlrev_b32_e32 v236, 16, v2
	v_and_b32_e32 v219, 0xffff0000, v2
	v_lshlrev_b32_e32 v218, 16, v3
	v_and_b32_e32 v158, 0xffff0000, v3
	v_lshlrev_b32_e32 v243, 16, v4
	v_and_b32_e32 v220, 0xffff0000, v4
	v_lshlrev_b32_e32 v159, 16, v5
	v_and_b32_e32 v167, 0xffff0000, v5
	global_load_dwordx4 v[2:5], v[0:1], off offset:192
	s_waitcnt vmcnt(5)
	v_lshlrev_b32_e32 v172, 16, v6
	v_and_b32_e32 v168, 0xffff0000, v6
	v_lshlrev_b32_e32 v157, 16, v7
	v_and_b32_e32 v156, 0xffff0000, v7
	v_lshlrev_b32_e32 v173, 16, v8
	v_and_b32_e32 v169, 0xffff0000, v8
	v_lshlrev_b32_e32 v163, 16, v9
	v_and_b32_e32 v161, 0xffff0000, v9
	global_load_dwordx4 v[6:9], v[0:1], off offset:224
	global_load_dwordx4 v[36:39], v[0:1], off offset:320
	global_load_dwordx4 v[42:45], v[0:1], off offset:352
	global_load_dwordx4 v[52:55], v[0:1], off offset:288
	global_load_dwordx4 v[56:59], v[0:1], off offset:256
	v_mul_f32_e32 v247, v219, v219
	v_fmac_f32_e32 v247, v236, v236
	v_fmac_f32_e32 v247, v218, v218
	v_fmac_f32_e32 v247, v158, v158
	v_fmac_f32_e32 v247, v243, v243
	v_fmac_f32_e32 v247, v220, v220
	v_fmac_f32_e32 v247, v159, v159
	v_fmac_f32_e32 v247, v167, v167
	v_fmac_f32_e32 v247, v172, v172
	v_fmac_f32_e32 v247, v168, v168
	v_fmac_f32_e32 v247, v157, v157
	v_fmac_f32_e32 v247, v156, v156
	v_fmac_f32_e32 v247, v173, v173
	v_fmac_f32_e32 v247, v169, v169
	v_fmac_f32_e32 v247, v163, v163
	v_fmac_f32_e32 v247, v161, v161
	s_waitcnt vmcnt(9)
	v_lshlrev_b32_e32 v165, 16, v10
	v_and_b32_e32 v164, 0xffff0000, v10
	v_fmac_f32_e32 v247, v165, v165
	v_lshlrev_b32_e32 v162, 16, v11
	v_fmac_f32_e32 v247, v164, v164
	v_and_b32_e32 v160, 0xffff0000, v11
	v_fmac_f32_e32 v247, v162, v162
	v_lshlrev_b32_e32 v166, 16, v12
	v_fmac_f32_e32 v247, v160, v160
	v_and_b32_e32 v212, 0xffff0000, v12
	v_fmac_f32_e32 v247, v166, v166
	v_lshlrev_b32_e32 v208, 16, v13
	v_fmac_f32_e32 v247, v212, v212
	v_and_b32_e32 v204, 0xffff0000, v13
	v_fmac_f32_e32 v247, v208, v208
	v_fmac_f32_e32 v247, v204, v204
	s_waitcnt vmcnt(8)
	v_lshlrev_b32_e32 v213, 16, v14
	v_and_b32_e32 v209, 0xffff0000, v14
	v_fmac_f32_e32 v247, v213, v213
	v_lshlrev_b32_e32 v175, 16, v15
	v_fmac_f32_e32 v247, v209, v209
	v_and_b32_e32 v171, 0xffff0000, v15
	v_fmac_f32_e32 v247, v175, v175
	v_lshlrev_b32_e32 v217, 16, v16
	v_fmac_f32_e32 v247, v171, v171
	v_and_b32_e32 v214, 0xffff0000, v16
	v_fmac_f32_e32 v247, v217, v217
	v_lshlrev_b32_e32 v206, 16, v17
	v_fmac_f32_e32 v247, v214, v214
	v_and_b32_e32 v196, 0xffff0000, v17
	v_fmac_f32_e32 v247, v206, v206
	v_fmac_f32_e32 v247, v196, v196
	s_waitcnt vmcnt(7)
	v_lshlrev_b32_e32 v215, 16, v18
	v_and_b32_e32 v210, 0xffff0000, v18
	v_fmac_f32_e32 v247, v215, v215
	v_lshlrev_b32_e32 v205, 16, v19
	v_fmac_f32_e32 v247, v210, v210
	v_and_b32_e32 v170, 0xffff0000, v19
	v_fmac_f32_e32 v247, v205, v205
	v_lshlrev_b32_e32 v216, 16, v20
	v_fmac_f32_e32 v247, v170, v170
	v_and_b32_e32 v211, 0xffff0000, v20
	v_fmac_f32_e32 v247, v216, v216
	v_lshlrev_b32_e32 v207, 16, v21
	v_fmac_f32_e32 v247, v211, v211
	v_and_b32_e32 v174, 0xffff0000, v21
	v_fmac_f32_e32 v247, v207, v207
	v_fmac_f32_e32 v247, v174, v174
	s_waitcnt vmcnt(6)
	v_lshlrev_b32_e32 v240, 16, v22
	v_and_b32_e32 v233, 0xffff0000, v22
	v_fmac_f32_e32 v247, v240, v240
	v_lshlrev_b32_e32 v227, 16, v23
	v_fmac_f32_e32 v247, v233, v233
	v_and_b32_e32 v221, 0xffff0000, v23
	v_fmac_f32_e32 v247, v227, v227
	v_lshlrev_b32_e32 v244, 16, v24
	v_fmac_f32_e32 v247, v221, v221
	v_and_b32_e32 v237, 0xffff0000, v24
	v_fmac_f32_e32 v247, v244, v244
	v_lshlrev_b32_e32 v230, 16, v25
	v_fmac_f32_e32 v247, v237, v237
	v_and_b32_e32 v224, 0xffff0000, v25
	v_fmac_f32_e32 v247, v230, v230
	v_fmac_f32_e32 v247, v224, v224
	s_waitcnt vmcnt(5)
	v_lshlrev_b32_e32 v241, 16, v2
	v_and_b32_e32 v234, 0xffff0000, v2
	v_fmac_f32_e32 v247, v241, v241
	v_lshlrev_b32_e32 v228, 16, v3
	v_fmac_f32_e32 v247, v234, v234
	v_and_b32_e32 v222, 0xffff0000, v3
	v_fmac_f32_e32 v247, v228, v228
	v_lshlrev_b32_e32 v245, 16, v4
	v_fmac_f32_e32 v247, v222, v222
	v_and_b32_e32 v238, 0xffff0000, v4
	v_fmac_f32_e32 v247, v245, v245
	v_lshlrev_b32_e32 v231, 16, v5
	v_fmac_f32_e32 v247, v238, v238
	v_and_b32_e32 v225, 0xffff0000, v5
	v_fmac_f32_e32 v247, v231, v231
	v_fmac_f32_e32 v247, v225, v225
	s_waitcnt vmcnt(4)
	v_lshlrev_b32_e32 v242, 16, v6
	v_and_b32_e32 v235, 0xffff0000, v6
	v_fmac_f32_e32 v247, v242, v242
	v_lshlrev_b32_e32 v229, 16, v7
	v_fmac_f32_e32 v247, v235, v235
	v_and_b32_e32 v223, 0xffff0000, v7
	v_fmac_f32_e32 v247, v229, v229
	v_lshlrev_b32_e32 v246, 16, v8
	v_fmac_f32_e32 v247, v223, v223
	v_add_u32_e32 v0, 0, v46
	v_and_b32_e32 v239, 0xffff0000, v8
	v_fmac_f32_e32 v247, v246, v246
	v_add_u32_e32 v248, 0x1e800, v0
	v_lshlrev_b32_e32 v232, 16, v9
	v_and_b32_e32 v226, 0xffff0000, v9
	v_fmac_f32_e32 v247, v239, v239
	ds_read_b128 v[92:95], v248
	ds_read_b128 v[88:91], v248 offset:16
	ds_read_b128 v[84:87], v248 offset:64
	ds_read_b128 v[80:83], v248 offset:80
	ds_read_b128 v[76:79], v248 offset:128
	ds_read_b128 v[72:75], v248 offset:144
	ds_read_b128 v[68:71], v248 offset:192
	ds_read_b128 v[48:51], v248 offset:208
	ds_read_b128 v[32:35], v248 offset:256
	ds_read_b128 v[28:31], v248 offset:272
	ds_read_b128 v[24:27], v248 offset:320
	ds_read_b128 v[20:23], v248 offset:336
	ds_read_b128 v[12:15], v248 offset:512
	ds_read_b128 v[8:11], v248 offset:528
	ds_read_b128 v[4:7], v248 offset:576
	ds_read_b128 v[0:3], v248 offset:592
	ds_read_b128 v[16:19], v248 offset:640
	ds_read_b128 v[96:99], v248 offset:656
	ds_read_b128 v[60:63], v248 offset:704
	ds_read_b128 v[64:67], v248 offset:720
	v_fmac_f32_e32 v247, v232, v232
	s_waitcnt vmcnt(0)
	v_lshlrev_b32_e32 v147, 16, v56
	v_lshlrev_b32_e32 v146, 16, v36
	v_fmac_f32_e32 v247, v226, v226
	v_lshlrev_b32_e32 v142, 16, v37
	v_and_b32_e32 v144, 0xffff0000, v37
	v_and_b32_e32 v149, 0xffff0000, v56
	v_and_b32_e32 v148, 0xffff0000, v36
	v_pk_mul_f32 v[36:37], v[146:147], v[146:147]
	v_lshlrev_b32_e32 v143, 16, v57
	v_and_b32_e32 v145, 0xffff0000, v57
	v_add_f32_e32 v37, v37, v247
	v_pk_mul_f32 v[56:57], v[148:149], v[148:149]
	s_waitcnt lgkmcnt(1)
	v_mov_b32_e32 v130, v60
	v_mov_b32_e32 v131, v4
	v_mov_b32_e32 v4, v61
	v_pk_mul_f32 v[60:61], v[142:143], v[142:143]
	v_add_f32_e32 v37, v57, v37
	v_mov_b32_e32 v124, v62
	v_mov_b32_e32 v125, v6
	v_mov_b32_e32 v6, v63
	v_lshlrev_b32_e32 v139, 16, v58
	v_lshlrev_b32_e32 v138, 16, v38
	v_pk_mul_f32 v[62:63], v[144:145], v[144:145]
	v_add_f32_e32 v37, v61, v37
	v_pk_mul_f32 v[46:47], v[138:139], v[138:139]
	v_and_b32_e32 v141, 0xffff0000, v58
	v_and_b32_e32 v140, 0xffff0000, v38
	v_add_f32_e32 v37, v63, v37
	v_lshlrev_b32_e32 v135, 16, v59
	v_lshlrev_b32_e32 v134, 16, v39
	v_and_b32_e32 v136, 0xffff0000, v39
	v_pk_mul_f32 v[38:39], v[140:141], v[140:141]
	v_add_f32_e32 v37, v47, v37
	v_lshlrev_b32_e32 v110, 16, v45
	v_and_b32_e32 v114, 0xffff0000, v45
	v_lshlrev_b32_e32 v116, 16, v44
	v_and_b32_e32 v120, 0xffff0000, v44
	v_pk_mul_f32 v[44:45], v[134:135], v[134:135]
	v_and_b32_e32 v137, 0xffff0000, v59
	v_add_f32_e32 v37, v39, v37
	v_lshlrev_b32_e32 v123, 16, v53
	v_and_b32_e32 v127, 0xffff0000, v53
	v_lshlrev_b32_e32 v129, 16, v52
	v_lshlrev_b32_e32 v128, 16, v42
	v_and_b32_e32 v133, 0xffff0000, v52
	v_pk_mul_f32 v[52:53], v[136:137], v[136:137]
	v_add_f32_e32 v37, v45, v37
	v_lshlrev_b32_e32 v111, 16, v55
	v_and_b32_e32 v115, 0xffff0000, v55
	v_lshlrev_b32_e32 v117, 16, v54
	v_and_b32_e32 v121, 0xffff0000, v54
	v_pk_mul_f32 v[54:55], v[128:129], v[128:129]
	v_and_b32_e32 v132, 0xffff0000, v42
	v_add_f32_e32 v37, v53, v37
	v_lshlrev_b32_e32 v122, 16, v43
	v_and_b32_e32 v126, 0xffff0000, v43
	v_pk_mul_f32 v[42:43], v[132:133], v[132:133]
	v_add_f32_e32 v37, v55, v37
	v_pk_mul_f32 v[40:41], v[122:123], v[122:123]
	v_add_f32_e32 v37, v43, v37
	v_pk_mul_f32 v[202:203], v[126:127], v[126:127]
	v_add_f32_e32 v37, v41, v37
	v_pk_mul_f32 v[154:155], v[116:117], v[116:117]
	v_add_f32_e32 v37, v203, v37
	v_pk_mul_f32 v[200:201], v[120:121], v[120:121]
	v_add_f32_e32 v37, v155, v37
	v_add_f32_e32 v37, v201, v37
	v_fmac_f32_e32 v37, v111, v111
	v_fmac_f32_e32 v37, v115, v115
	v_add_f32_e32 v36, v36, v37
	v_add_f32_e32 v36, v56, v36
	v_add_f32_e32 v36, v60, v36
	v_add_f32_e32 v36, v62, v36
	v_add_f32_e32 v36, v46, v36
	v_add_f32_e32 v36, v38, v36
	v_add_f32_e32 v41, v44, v36
	v_add_f32_e32 v41, v52, v41
	v_add_f32_e32 v41, v54, v41
	v_add_f32_e32 v41, v42, v41
	s_waitcnt lgkmcnt(0)
	v_mov_b32_e32 v112, v66
	v_mov_b32_e32 v113, v2
	v_mov_b32_e32 v2, v67
	v_mov_b32_e32 v118, v64
	v_mov_b32_e32 v119, v0
	v_mov_b32_e32 v0, v65
	global_load_dwordx4 v[64:67], v[150:151], off
	global_load_dwordx4 v[56:59], v[150:151], off offset:16
	global_load_dwordx4 v[60:63], v[152:153], off offset:16
	global_load_dwordx4 v[44:47], v[150:151], off offset:64
	global_load_dwordx4 v[36:39], v[150:151], off offset:80
	v_add_f32_e32 v150, v40, v41
	v_add_f32_e32 v155, v202, v150
	v_mov_b32_e32 v150, v114
	v_mov_b32_e32 v151, v110
	v_add_f32_e32 v154, v154, v155
	v_pk_mul_f32 v[150:151], v[150:151], v[150:151]
	v_add_f32_e32 v154, v200, v154
	v_add_f32_e32 v151, v151, v154
	v_add_f32_e32 v150, v150, v151
	v_mov_b32_e32 v151, v150
	s_nop 1
	v_permlane32_swap_b32_e32 v150, v151
	v_add_f32_e32 v150, v150, v151
	v_fmamk_f32 v150, v150, 0x3baaaaab, v197
	v_mul_f32_e32 v151, 0x4f800000, v150
	v_cmp_gt_f32_e32 vcc, s36, v150
	global_load_dwordx4 v[52:55], v[152:153], off offset:64
	global_load_dwordx4 v[40:43], v[152:153], off offset:80
	v_cndmask_b32_e32 v154, v150, v151, vcc
	v_sqrt_f32_e32 v155, v154
	v_mov_b32_e32 v150, v98
	v_mov_b32_e32 v151, v10
	v_mov_b32_e32 v10, v99
	v_add_u32_e32 v98, -1, v155
	v_fma_f32 v99, -v98, v155, v154
	v_cmp_ge_f32_e64 s[8:9], 0, v99
	v_add_u32_e32 v99, 1, v155
	s_nop 0
	v_cndmask_b32_e64 v98, v155, v98, s[8:9]
	v_fma_f32 v155, -v99, v155, v154
	v_cmp_lt_f32_e64 s[8:9], 0, v155
	v_mov_b32_e32 v155, v8
	v_mov_b32_e32 v8, v97
	v_cndmask_b32_e64 v98, v98, v99, s[8:9]
	v_mul_f32_e32 v99, 0x37800000, v98
	v_cndmask_b32_e32 v98, v98, v99, vcc
	v_cmp_class_f32_e32 vcc, v154, v198
	s_nop 1
	v_cndmask_b32_e32 v200, v98, v154, vcc
	v_div_scale_f32 v201, s[8:9], v200, v200, 1.0
	v_rcp_f32_e32 v202, v201
	v_mov_b32_e32 v154, v96
	v_div_scale_f32 v203, vcc, 1.0, v200, 1.0
	v_fma_f32 v96, -v201, v202, 1.0
	v_fmac_f32_e32 v202, v96, v202
	v_mul_f32_e32 v247, v203, v202
	v_fma_f32 v96, -v201, v247, v203
	v_fmac_f32_e32 v247, v96, v202
	global_load_dwordx4 v[96:99], v[152:153], off
	v_fma_f32 v152, -v201, v247, v203
	v_div_fmas_f32 v152, v152, v202, v247
	v_div_fixup_f32 v152, v152, v200, 1.0
	v_mul_f32_e32 v88, v88, v152
	v_mul_f32_e32 v200, v88, v243
	v_mul_f32_e32 v88, v93, v152
	v_mul_f32_e32 v93, v95, v152
	v_mul_f32_e32 v158, v93, v158
	v_mul_f32_e32 v93, v152, v48
	v_mul_f32_e32 v217, v93, v217
	v_mov_b32_e32 v93, v14
	v_mov_b32_e32 v14, v19
	v_mov_b32_e32 v19, v12
	v_mul_f32_e32 v12, v152, v32
	v_mul_f32_e32 v215, v12, v215
	v_mul_f32_e32 v12, v152, v28
	v_mul_f32_e32 v216, v12, v216
	v_mul_f32_e32 v12, v152, v33
	v_mul_f32_e32 v210, v12, v210
	v_mul_f32_e32 v12, v152, v29
	v_mul_f32_e32 v211, v12, v211
	v_mul_f32_e32 v12, v152, v34
	v_mul_f32_e32 v201, v88, v219
	v_mul_f32_e32 v88, v89, v152
	v_mul_f32_e32 v205, v12, v205
	v_mul_f32_e32 v12, v152, v30
	v_mul_f32_e32 v92, v92, v152
	v_mul_f32_e32 v202, v88, v220
	v_mul_f32_e32 v220, v152, v73
	v_mul_f32_e32 v207, v12, v207
	v_mul_f32_e32 v12, v152, v35
	v_mul_f32_e32 v153, v92, v236
	v_mul_f32_e32 v236, v152, v74
	v_mul_f32_e32 v212, v220, v212
	v_mul_f32_e32 v220, v12, v170
	v_mul_f32_e32 v12, v152, v31
	v_mul_f32_e32 v208, v236, v208
	v_mul_f32_e32 v236, v12, v174
	v_mul_f32_e32 v12, v152, v24
	v_mul_f32_e32 v243, v152, v75
	v_mul_f32_e32 v240, v12, v240
	v_mul_f32_e32 v12, v152, v20
	v_mul_f32_e32 v204, v243, v204
	v_mul_f32_e32 v243, v12, v244
	v_mul_f32_e32 v12, v152, v25
	v_mul_f32_e32 v233, v12, v233
	v_mul_f32_e32 v12, v152, v21
	v_mul_f32_e32 v92, v94, v152
	v_mul_f32_e32 v94, v152, v72
	v_mul_f32_e32 v247, v152, v68
	v_mul_f32_e32 v249, v152, v69
	v_mul_f32_e32 v250, v152, v70
	v_mul_f32_e32 v251, v152, v71
	ds_read_b128 v[68:71], v248 offset:384
	ds_read_b128 v[72:75], v248 offset:400
	v_mul_f32_e32 v237, v12, v237
	v_mul_f32_e32 v12, v152, v26
	v_mul_f32_e32 v227, v12, v227
	v_mul_f32_e32 v12, v152, v22
	v_mul_f32_e32 v230, v12, v230
	v_mul_f32_e32 v12, v152, v27
	v_mul_f32_e32 v221, v12, v221
	v_mul_f32_e32 v12, v152, v23
	v_mul_f32_e32 v224, v12, v224
	s_waitcnt lgkmcnt(1)
	v_mul_f32_e32 v12, v152, v68
	v_mul_f32_e32 v68, v12, v241
	s_waitcnt lgkmcnt(0)
	v_mul_f32_e32 v12, v152, v72
	v_mul_f32_e32 v72, v12, v245
	v_mul_f32_e32 v12, v152, v69
	v_mul_f32_e32 v80, v80, v152
	v_mul_f32_e32 v81, v81, v152
	v_mul_f32_e32 v69, v12, v234
	v_mul_f32_e32 v12, v152, v73
	v_mul_f32_e32 v203, v92, v218
	v_mul_f32_e32 v88, v90, v152
	v_mul_f32_e32 v89, v91, v152
	v_mul_f32_e32 v90, v82, v152
	v_mul_f32_e32 v91, v83, v152
	v_mul_f32_e32 v92, v76, v152
	v_mul_f32_e32 v95, v77, v152
	v_mul_f32_e32 v218, v78, v152
	v_mul_f32_e32 v219, v79, v152
	v_mul_f32_e32 v253, v80, v173
	v_mul_f32_e32 v254, v81, v169
	ds_read_b128 v[76:79], v248 offset:448
	ds_read_b128 v[80:83], v248 offset:464
	v_mul_f32_e32 v73, v12, v238
	v_mul_f32_e32 v12, v152, v70
	v_mul_f32_e32 v70, v12, v228
	v_mul_f32_e32 v12, v152, v74
	v_mul_f32_e32 v74, v12, v231
	v_mul_f32_e32 v12, v152, v71
	v_mul_f32_e32 v71, v12, v222
	v_mul_f32_e32 v12, v152, v75
	v_mul_f32_e32 v75, v12, v225
	s_waitcnt lgkmcnt(1)
	v_mul_f32_e32 v12, v152, v76
	v_mul_f32_e32 v76, v12, v242
	s_waitcnt lgkmcnt(0)
	v_mul_f32_e32 v12, v152, v80
	v_mul_f32_e32 v80, v12, v246
	v_mul_f32_e32 v12, v152, v77
	v_mul_f32_e32 v77, v12, v235
	v_mul_f32_e32 v12, v152, v81
	v_mul_f32_e32 v81, v12, v239
	v_mul_f32_e32 v12, v152, v78
	v_mul_f32_e32 v78, v12, v229
	v_mul_f32_e32 v12, v152, v82
	v_mul_f32_e32 v82, v12, v232
	v_mul_f32_e32 v12, v152, v79
	v_mul_f32_e32 v165, v92, v165
	v_mov_b32_e32 v92, v18
	v_mov_b32_e32 v18, v16
	v_mul_f32_e32 v79, v12, v223
	v_mul_f32_e32 v12, v152, v83
	v_mul_f32_e32 v83, v12, v226
	v_pk_mul_f32 v[18:19], v[152:153], v[18:19] op_sel_hi:[0,1]
	v_mov_b32_e32 v12, v17
	s_waitcnt vmcnt(7)
	v_mov_b32_e32 v28, v64
	s_waitcnt vmcnt(0)
	v_mov_b32_e32 v29, v96
	v_pk_mul_f32 v[18:19], v[18:19], v[146:147]
	v_pk_mul_f32 v[12:13], v[152:153], v[12:13] op_sel_hi:[0,1]
	v_mov_b32_e32 v34, v96
	v_mov_b32_e32 v35, v64
	v_pk_mul_f32 v[12:13], v[12:13], v[148:149]
	v_pk_mul_f32 v[34:35], v[18:19], v[34:35]
	v_pk_mul_f32 v[18:19], v[18:19], v[28:29]
	v_mov_b32_e32 v64, v97
	v_mov_b32_e32 v96, v65
	v_pk_mul_f32 v[16:17], v[152:153], v[92:93] op_sel_hi:[0,1]
	v_add_f32_e32 v28, v18, v19
	v_pk_mul_f32 v[18:19], v[12:13], v[64:65]
	v_pk_mul_f32 v[12:13], v[12:13], v[96:97]
	v_pk_mul_f32 v[16:17], v[16:17], v[142:143]
	v_sub_f32_e32 v18, v19, v18
	v_add_f32_e32 v19, v12, v13
	v_mov_b32_e32 v12, v98
	v_mov_b32_e32 v13, v66
	v_mul_f32_e32 v166, v94, v166
	v_mul_f32_e32 v164, v95, v164
	v_mov_b32_e32 v94, v66
	v_mov_b32_e32 v95, v98
	v_pk_mul_f32 v[14:15], v[152:153], v[14:15] op_sel_hi:[0,1]
	v_pk_mul_f32 v[12:13], v[16:17], v[12:13]
	v_pk_mul_f32 v[14:15], v[14:15], v[144:145]
	v_sub_f32_e32 v29, v13, v12
	v_pk_mul_f32 v[12:13], v[16:17], v[94:95]
	v_mov_b32_e32 v66, v99
	v_add_f32_e32 v16, v12, v13
	v_pk_mul_f32 v[12:13], v[14:15], v[66:67]
	v_mov_b32_e32 v98, v67
	v_pk_mul_f32 v[20:21], v[152:153], v[154:155] op_sel_hi:[0,1]
	v_sub_f32_e32 v17, v13, v12
	v_pk_mul_f32 v[12:13], v[14:15], v[98:99]
	v_pk_mul_f32 v[20:21], v[20:21], v[138:139]
	v_add_f32_e32 v14, v12, v13
	v_mov_b32_e32 v12, v60
	v_mov_b32_e32 v13, v56
	v_mul_f32_e32 v163, v90, v163
	v_mul_f32_e32 v161, v91, v161
	v_mov_b32_e32 v90, v56
	v_mov_b32_e32 v91, v60
	v_pk_mul_f32 v[8:9], v[152:153], v[8:9] op_sel_hi:[0,1]
	v_pk_mul_f32 v[12:13], v[20:21], v[12:13]
	v_pk_mul_f32 v[8:9], v[8:9], v[140:141]
	v_sub_f32_e32 v15, v13, v12
	v_pk_mul_f32 v[12:13], v[20:21], v[90:91]
	v_mov_b32_e32 v56, v61
	v_mov_b32_e32 v60, v57
	v_pk_mul_f32 v[22:23], v[152:153], v[150:151] op_sel_hi:[0,1]
	v_add_f32_e32 v20, v12, v13
	v_pk_mul_f32 v[12:13], v[8:9], v[56:57]
	v_pk_mul_f32 v[8:9], v[8:9], v[60:61]
	v_pk_mul_f32 v[22:23], v[22:23], v[134:135]
	v_sub_f32_e32 v12, v13, v12
	v_add_f32_e32 v13, v8, v9
	v_mov_b32_e32 v8, v62
	v_mov_b32_e32 v9, v58
	v_mul_f32_e32 v159, v88, v159
	v_mul_f32_e32 v167, v89, v167
	v_mov_b32_e32 v88, v58
	v_mov_b32_e32 v89, v62
	v_pk_mul_f32 v[10:11], v[152:153], v[10:11] op_sel_hi:[0,1]
	v_pk_mul_f32 v[8:9], v[22:23], v[8:9]
	v_pk_mul_f32 v[10:11], v[10:11], v[136:137]
	v_sub_f32_e32 v21, v9, v8
	v_pk_mul_f32 v[8:9], v[22:23], v[88:89]
	v_mov_b32_e32 v58, v63
	v_add_f32_e32 v22, v8, v9
	v_pk_mul_f32 v[8:9], v[10:11], v[58:59]
	v_mov_b32_e32 v62, v59
	v_pk_mul_f32 v[24:25], v[152:153], v[130:131] op_sel_hi:[0,1]
	v_sub_f32_e32 v23, v9, v8
	v_pk_mul_f32 v[8:9], v[10:11], v[62:63]
	v_mul_f32_e32 v86, v86, v152
	v_mul_f32_e32 v87, v87, v152
	v_pk_mul_f32 v[24:25], v[24:25], v[128:129]
	v_add_f32_e32 v10, v8, v9
	v_mov_b32_e32 v8, v52
	v_mov_b32_e32 v9, v44
	v_mul_f32_e32 v157, v86, v157
	v_mul_f32_e32 v156, v87, v156
	v_mov_b32_e32 v86, v44
	v_mov_b32_e32 v87, v52
	v_pk_mul_f32 v[4:5], v[152:153], v[4:5] op_sel_hi:[0,1]
	v_pk_mul_f32 v[8:9], v[24:25], v[8:9]
	v_pk_mul_f32 v[4:5], v[4:5], v[132:133]
	v_sub_f32_e32 v11, v9, v8
	v_pk_mul_f32 v[8:9], v[24:25], v[86:87]
	v_mov_b32_e32 v44, v53
	v_mov_b32_e32 v52, v45
	v_pk_mul_f32 v[30:31], v[152:153], v[124:125] op_sel_hi:[0,1]
	v_add_f32_e32 v24, v8, v9
	v_pk_mul_f32 v[8:9], v[4:5], v[44:45]
	v_pk_mul_f32 v[4:5], v[4:5], v[52:53]
	v_mul_f32_e32 v84, v84, v152
	v_mul_f32_e32 v85, v85, v152
	v_pk_mul_f32 v[30:31], v[30:31], v[122:123]
	v_sub_f32_e32 v8, v9, v8
	v_add_f32_e32 v9, v4, v5
	v_mov_b32_e32 v4, v54
	v_mov_b32_e32 v5, v46
	v_mul_f32_e32 v252, v84, v172
	v_mul_f32_e32 v168, v85, v168
	v_mov_b32_e32 v84, v46
	v_mov_b32_e32 v85, v54
	v_pk_mul_f32 v[6:7], v[152:153], v[6:7] op_sel_hi:[0,1]
	v_pk_mul_f32 v[4:5], v[30:31], v[4:5]
	v_pk_mul_f32 v[6:7], v[6:7], v[126:127]
	v_sub_f32_e32 v25, v5, v4
	v_pk_mul_f32 v[4:5], v[30:31], v[84:85]
	v_mov_b32_e32 v46, v55
	v_add_f32_e32 v30, v4, v5
	v_pk_mul_f32 v[4:5], v[6:7], v[46:47]
	v_mov_b32_e32 v54, v47
	v_pk_mul_f32 v[26:27], v[152:153], v[118:119] op_sel_hi:[0,1]
	v_sub_f32_e32 v31, v5, v4
	v_pk_mul_f32 v[4:5], v[6:7], v[54:55]
	v_pk_mul_f32 v[26:27], v[26:27], v[116:117]
	v_add_f32_e32 v6, v4, v5
	v_mov_b32_e32 v4, v40
	v_mov_b32_e32 v5, v36
	v_mul_f32_e32 v172, v152, v50
	v_mul_f32_e32 v173, v152, v51
	v_mov_b32_e32 v50, v36
	v_mov_b32_e32 v51, v40
	v_pk_mul_f32 v[0:1], v[152:153], v[0:1] op_sel_hi:[0,1]
	v_pk_mul_f32 v[4:5], v[26:27], v[4:5]
	v_pk_mul_f32 v[0:1], v[0:1], v[120:121]
	v_sub_f32_e32 v7, v5, v4
	v_pk_mul_f32 v[4:5], v[26:27], v[50:51]
	v_mov_b32_e32 v36, v41
	v_mov_b32_e32 v40, v37
	v_pk_mul_f32 v[32:33], v[152:153], v[112:113] op_sel_hi:[0,1]
	v_add_f32_e32 v26, v4, v5
	v_pk_mul_f32 v[4:5], v[0:1], v[36:37]
	v_pk_mul_f32 v[0:1], v[0:1], v[40:41]
	v_pk_mul_f32 v[32:33], v[32:33], v[110:111]
	v_sub_f32_e32 v4, v5, v4
	v_add_f32_e32 v5, v0, v1
	v_mov_b32_e32 v0, v42
	v_mov_b32_e32 v1, v38
	v_mul_f32_e32 v169, v152, v49
	v_mov_b32_e32 v48, v38
	v_mov_b32_e32 v49, v42
	v_pk_mul_f32 v[2:3], v[152:153], v[2:3] op_sel_hi:[0,1]
	v_pk_mul_f32 v[0:1], v[32:33], v[0:1]
	v_pk_mul_f32 v[2:3], v[2:3], v[114:115]
	v_sub_f32_e32 v27, v1, v0
	v_pk_mul_f32 v[0:1], v[32:33], v[48:49]
	v_mov_b32_e32 v38, v43
	v_add_f32_e32 v32, v0, v1
	v_pk_mul_f32 v[0:1], v[2:3], v[38:39]
	v_mov_b32_e32 v42, v39
	v_sub_f32_e32 v33, v1, v0
	v_pk_mul_f32 v[0:1], v[2:3], v[42:43]
	v_mul_f32_e32 v162, v218, v162
	v_mul_f32_e32 v160, v219, v160
	v_add_f32_e32 v0, v0, v1
	v_mul_f32_e32 v213, v247, v213
	v_mul_f32_e32 v209, v249, v209
	v_mul_f32_e32 v214, v169, v214
	v_mul_f32_e32 v218, v250, v175
	v_mul_f32_e32 v206, v172, v206
	v_mul_f32_e32 v219, v251, v171
	v_mul_f32_e32 v196, v173, v196
	v_sub_f32_e32 v34, v35, v34
	v_cvt_pk_bf16_f32 v172, v153, v201
	v_cvt_pk_bf16_f32 v173, v203, v158
	v_cvt_pk_bf16_f32 v174, v200, v202
	v_cvt_pk_bf16_f32 v175, v159, v167
	v_cvt_pk_bf16_f32 v168, v252, v168
	v_cvt_pk_bf16_f32 v169, v157, v156
	v_cvt_pk_bf16_f32 v170, v253, v254
	v_cvt_pk_bf16_f32 v171, v163, v161
	v_cvt_pk_bf16_f32 v164, v165, v164
	v_cvt_pk_bf16_f32 v165, v162, v160
	v_cvt_pk_bf16_f32 v166, v166, v212
	v_cvt_pk_bf16_f32 v167, v208, v204
	v_cvt_pk_bf16_f32 v160, v213, v209
	v_cvt_pk_bf16_f32 v161, v218, v219
	v_cvt_pk_bf16_f32 v162, v217, v214
	v_cvt_pk_bf16_f32 v163, v206, v196
	v_cvt_pk_bf16_f32 v156, v215, v210
	v_cvt_pk_bf16_f32 v157, v205, v220
	v_cvt_pk_bf16_f32 v158, v216, v211
	v_cvt_pk_bf16_f32 v159, v207, v236
	v_cvt_pk_bf16_f32 v152, v240, v233
	v_cvt_pk_bf16_f32 v153, v227, v221
	v_cvt_pk_bf16_f32 v154, v243, v237
	v_cvt_pk_bf16_f32 v155, v230, v224
	v_cvt_pk_bf16_f32 v148, v68, v69
	v_cvt_pk_bf16_f32 v149, v70, v71
	v_cvt_pk_bf16_f32 v150, v72, v73
	v_cvt_pk_bf16_f32 v151, v74, v75
	v_cvt_pk_bf16_f32 v144, v76, v77
	v_cvt_pk_bf16_f32 v145, v78, v79
	v_cvt_pk_bf16_f32 v146, v80, v81
	v_cvt_pk_bf16_f32 v147, v82, v83
	v_cvt_pk_bf16_f32 v140, v34, v18
	v_cvt_pk_bf16_f32 v141, v29, v17
	v_cvt_pk_bf16_f32 v142, v15, v12
	v_cvt_pk_bf16_f32 v143, v21, v23
	v_cvt_pk_bf16_f32 v136, v11, v8
	v_cvt_pk_bf16_f32 v137, v25, v31
	v_cvt_pk_bf16_f32 v138, v7, v4
	v_cvt_pk_bf16_f32 v139, v27, v33
	v_cvt_pk_bf16_f32 v132, v28, v19
	v_cvt_pk_bf16_f32 v133, v16, v14
	v_cvt_pk_bf16_f32 v134, v20, v13
	v_cvt_pk_bf16_f32 v135, v22, v10
	v_cvt_pk_bf16_f32 v128, v24, v9
	v_cvt_pk_bf16_f32 v129, v30, v6
	v_cvt_pk_bf16_f32 v130, v26, v5
	v_cvt_pk_bf16_f32 v131, v32, v0
	v_mov_b32_e32 v0, s4
	v_mad_u32_u24 v48, v190, s35, v0
	v_bfe_u32 v20, v195, 1, 3
	v_bitop3_b32 v0, v191, v194, 7 bitop3:0x78
	v_lshl_add_u32 v206, v0, 4, v48
	v_bitop3_b32 v0, v191, v20, 2 bitop3:0x36
	v_lshl_add_u32 v207, v0, 4, v48
	v_bitop3_b32 v0, v191, v20, 4 bitop3:0x36
	s_waitcnt vmcnt(0) lgkmcnt(0)
	s_barrier
	v_lshl_add_u32 v208, v0, 4, v48
	v_lshl_add_u64 v[0:1], s[96:97], 0, v[100:101]
	s_add_i32 s4, s49, 0xc000
	s_mov_b32 s8, m0
	s_mov_b32 m0, s4
	s_nop 0
	global_load_lds_dwordx4 v[0:1], off
	s_mov_b32 m0, s8
	v_lshl_add_u64 v[0:1], s[96:97], 0, v[102:103]
	s_add_i32 s4, s49, 0xe000
	s_mov_b32 s8, m0
	s_mov_b32 m0, s4
	s_nop 0
	global_load_lds_dwordx4 v[0:1], off
	s_mov_b32 m0, s8
	v_lshl_add_u64 v[0:1], s[96:97], 0, v[104:105]
	s_add_i32 s4, s49, 0x10000
	s_mov_b32 s8, m0
	s_mov_b32 m0, s4
	s_nop 0
	global_load_lds_dwordx4 v[0:1], off
	s_mov_b32 m0, s8
	v_lshl_add_u64 v[0:1], s[44:45], 0, v[106:107]
	s_add_i32 s4, s49, 0x16000
	s_mov_b32 s8, m0
	s_mov_b32 m0, s4
	s_nop 0
	global_load_lds_dwordx4 v[0:1], off
	s_mov_b32 m0, s8
	v_lshl_add_u64 v[0:1], s[44:45], 0, v[108:109]
	s_add_i32 s4, s49, 0x18000
	s_mov_b32 s8, m0
	s_mov_b32 m0, s4
	s_nop 0
	global_load_lds_dwordx4 v[0:1], off
	s_mov_b32 m0, s8
	ds_read_b128 v[0:3], v206 offset:0
	ds_read_b128 v[16:19], v206 offset:12288
	ds_read_b128 v[32:35], v207 offset:0
	ds_read_b128 v[36:39], v207 offset:12288
	ds_read_b128 v[40:43], v208 offset:0
	ds_read_b128 v[44:47], v208 offset:12288
	v_bitop3_b32 v49, v191, v20, 6 bitop3:0x36
	s_waitcnt lgkmcnt(4)
	v_lshl_add_u32 v209, v49, 4, v48
	v_mfma_f32_32x32x16_bf16 v[0:15], v[0:3], v[172:175], 0
	ds_read_b128 v[48:51], v209 offset:0
	ds_read_b128 v[52:55], v209 offset:12288
	s_waitcnt lgkmcnt(4)
	v_and_b32_e32 v194, 63, v195
	s_mov_b32 s4, 2
	v_cmp_gt_u32_e64 s[8:9], 32, v194
	v_mov_b32_e32 v211, 0
	v_mfma_f32_32x32x16_bf16 v[16:31], v[16:19], v[172:175], 0
	v_mfma_f32_32x32x16_bf16 v[0:15], v[32:35], v[168:171], v[0:15]
	ds_read_b128 v[32:35], v206 offset:128
	v_mfma_f32_32x32x16_bf16 v[16:31], v[36:39], v[168:171], v[16:31]
	ds_read_b128 v[36:39], v206 offset:12416
	s_waitcnt lgkmcnt(4)
	s_nop 0
	v_mfma_f32_32x32x16_bf16 v[0:15], v[40:43], v[164:167], v[0:15]
	ds_read_b128 v[40:43], v207 offset:128
	v_mfma_f32_32x32x16_bf16 v[16:31], v[44:47], v[164:167], v[16:31]
	ds_read_b128 v[44:47], v207 offset:12416
	s_waitcnt lgkmcnt(4)
	s_nop 0
	v_mfma_f32_32x32x16_bf16 v[0:15], v[48:51], v[160:163], v[0:15]
	ds_read_b128 v[48:51], v208 offset:128
	v_mfma_f32_32x32x16_bf16 v[16:31], v[52:55], v[160:163], v[16:31]
	ds_read_b128 v[52:55], v208 offset:12416
	s_waitcnt lgkmcnt(4)
	s_nop 0
	v_mfma_f32_32x32x16_bf16 v[0:15], v[32:35], v[156:159], v[0:15]
	ds_read_b128 v[32:35], v209 offset:128
	v_mfma_f32_32x32x16_bf16 v[16:31], v[36:39], v[156:159], v[16:31]
	ds_read_b128 v[36:39], v209 offset:12416
	s_waitcnt lgkmcnt(4)
	s_nop 0
	v_mfma_f32_32x32x16_bf16 v[0:15], v[40:43], v[152:155], v[0:15]
	ds_read_b128 v[40:43], v206 offset:256
	v_mfma_f32_32x32x16_bf16 v[16:31], v[44:47], v[152:155], v[16:31]
	ds_read_b128 v[44:47], v206 offset:12544
	s_waitcnt lgkmcnt(4)
	s_nop 0
	v_mfma_f32_32x32x16_bf16 v[0:15], v[48:51], v[148:151], v[0:15]
	ds_read_b128 v[48:51], v207 offset:256
	v_mfma_f32_32x32x16_bf16 v[16:31], v[52:55], v[148:151], v[16:31]
	ds_read_b128 v[52:55], v207 offset:12544
	s_waitcnt lgkmcnt(4)
	s_nop 0
	v_mfma_f32_32x32x16_bf16 v[0:15], v[32:35], v[144:147], v[0:15]
	ds_read_b128 v[32:35], v208 offset:256
	v_mfma_f32_32x32x16_bf16 v[16:31], v[36:39], v[144:147], v[16:31]
	ds_read_b128 v[36:39], v208 offset:12544
	s_waitcnt lgkmcnt(4)
	s_nop 0
	v_mfma_f32_32x32x16_bf16 v[0:15], v[40:43], v[140:143], v[0:15]
	ds_read_b128 v[40:43], v209 offset:256
	ds_read_b128 v[56:59], v209 offset:12544
	s_waitcnt lgkmcnt(4)
	s_waitcnt lgkmcnt(2)
	s_nop 0
	s_waitcnt lgkmcnt(0)
	s_waitcnt vmcnt(5) lgkmcnt(0)
	s_barrier
	v_mfma_f32_32x32x16_bf16 v[0:15], v[48:51], v[136:139], v[0:15]
	v_mfma_f32_32x32x16_bf16 v[16:31], v[44:47], v[140:143], v[16:31]
	v_lshlrev_b32_e32 v45, 4, v195
	v_lshlrev_b32_e32 v44, 3, v194
	v_and_b32_e32 v45, 0xc0, v45
	v_lshlrev_b32_e32 v46, 1, v195
	v_and_or_b32 v45, v44, 24, v45
	v_and_b32_e32 v46, 32, v46
	v_and_b32_e32 v44, 0x100, v44
	v_mfma_f32_32x32x16_bf16 v[0:15], v[32:35], v[132:135], v[0:15]
	v_or3_b32 v44, v45, v46, v44
	v_add_u32_e32 v196, s11, v44
	v_lshl_add_u32 v195, v190, 2, s48
	v_mfma_f32_32x32x16_bf16 v[16:31], v[52:55], v[136:139], v[16:31]
	v_mfma_f32_32x32x16_bf16 v[0:15], v[40:43], v[128:131], v[0:15]
	v_mfma_f32_32x32x16_bf16 v[16:31], v[36:39], v[132:135], v[16:31]
	s_nop 10
	v_max_f32_e32 v48, v1, v1
	v_max_f32_e32 v49, v0, v0
	v_max_f32_e32 v48, v49, v48
	v_max3_f32 v48, v48, v2, v3
	v_max3_f32 v48, v48, v4, v5
	v_max3_f32 v48, v48, v6, v7
	v_max3_f32 v48, v48, v8, v9
	v_mfma_f32_32x32x16_bf16 v[16:31], v[56:59], v[128:131], v[16:31]
	v_max3_f32 v48, v48, v10, v11
	v_max3_f32 v48, v48, v12, v13
	v_max3_f32 v48, v48, v14, v15
	v_mov_b64_e32 v[46:47], s[30:31]
	v_mov_b64_e32 v[44:45], s[28:29]
	v_mov_b64_e32 v[42:43], s[26:27]
	v_mov_b64_e32 v[40:41], s[24:25]
	s_nop 4
	v_max3_f32 v48, v48, v16, v17
	v_max3_f32 v48, v48, v18, v19
	v_max3_f32 v48, v48, v20, v21
	v_max3_f32 v48, v48, v22, v23
	v_max3_f32 v48, v48, v24, v25
	v_max3_f32 v48, v48, v26, v27
	v_max3_f32 v48, v48, v28, v29
	v_max3_f32 v48, v48, v30, v31
	v_mov_b32_e32 v49, v48
	s_nop 1
	v_permlane32_swap_b32_e32 v48, v49
	v_max_f32_e32 v49, v49, v49
	v_max_f32_e32 v48, v48, v48
	v_max_f32_e32 v48, v48, v49
	v_add_f32_e32 v49, 0x7149f2ca, v48
	v_max_f32_e32 v48, 0xf149f2ca, v48
	v_cmp_ge_f32_e32 vcc, s0, v49
	v_sub_f32_e32 v49, 0xf149f2ca, v48
	v_mul_f32_e32 v49, 0x3dd53b94, v49
	v_exp_f32_e32 v49, v49
	v_mov_b64_e32 v[38:39], s[22:23]
	v_mov_b64_e32 v[36:37], s[20:21]
	v_mov_b64_e32 v[34:35], s[18:19]
	v_mov_b64_e32 v[32:33], s[16:17]
	s_add_i32 s23, s52, 1
	s_cmp_eq_u64 vcc, exec
	s_cselect_b64 vcc, -1, 0
	v_cndmask_b32_e64 v210, v49, 1.0, vcc
	v_mov_b32_e32 v49, 0xf149f2ca
	v_cndmask_b32_e32 v204, v48, v49, vcc
	v_mul_f32_e32 v48, 0xbdd53b94, v204
	v_fmamk_f32 v0, v0, 0x3dd53b94, v48
	v_exp_f32_e32 v112, v0
	v_fmamk_f32 v0, v1, 0x3dd53b94, v48
	v_exp_f32_e32 v113, v0
	v_fmamk_f32 v0, v2, 0x3dd53b94, v48
	v_exp_f32_e32 v114, v0
	v_fmamk_f32 v0, v3, 0x3dd53b94, v48
	v_exp_f32_e32 v115, v0
	v_fmamk_f32 v0, v4, 0x3dd53b94, v48
	v_exp_f32_e32 v116, v0
	v_fmamk_f32 v0, v5, 0x3dd53b94, v48
	v_exp_f32_e32 v117, v0
	v_fmamk_f32 v0, v6, 0x3dd53b94, v48
	v_exp_f32_e32 v118, v0
	v_fmamk_f32 v0, v7, 0x3dd53b94, v48
	v_exp_f32_e32 v119, v0
	v_fmamk_f32 v0, v8, 0x3dd53b94, v48
	v_exp_f32_e32 v120, v0
	v_fmamk_f32 v0, v9, 0x3dd53b94, v48
	v_exp_f32_e32 v121, v0
	v_fmamk_f32 v0, v10, 0x3dd53b94, v48
	v_exp_f32_e32 v122, v0
	v_fmamk_f32 v0, v11, 0x3dd53b94, v48
	v_exp_f32_e32 v123, v0
	v_fmamk_f32 v0, v12, 0x3dd53b94, v48
	v_exp_f32_e32 v124, v0
	v_fmamk_f32 v0, v13, 0x3dd53b94, v48
	v_pk_fma_f32 v[110:111], v[30:31], s[68:69], v[48:49] op_sel_hi:[1,0,0]
	v_pk_fma_f32 v[108:109], v[28:29], s[68:69], v[48:49] op_sel_hi:[1,0,0]
	v_pk_fma_f32 v[106:107], v[26:27], s[68:69], v[48:49] op_sel_hi:[1,0,0]
	v_pk_fma_f32 v[104:105], v[24:25], s[68:69], v[48:49] op_sel_hi:[1,0,0]
	v_pk_fma_f32 v[102:103], v[22:23], s[68:69], v[48:49] op_sel_hi:[1,0,0]
	v_pk_fma_f32 v[100:101], v[20:21], s[68:69], v[48:49] op_sel_hi:[1,0,0]
	v_pk_fma_f32 v[98:99], v[18:19], s[68:69], v[48:49] op_sel_hi:[1,0,0]
	v_pk_fma_f32 v[96:97], v[16:17], s[68:69], v[48:49] op_sel_hi:[1,0,0]
	v_exp_f32_e32 v125, v0
	v_fmamk_f32 v0, v14, 0x3dd53b94, v48
	v_fmac_f32_e32 v48, 0x3dd53b94, v15
	v_exp_f32_e32 v126, v0
	v_exp_f32_e32 v127, v48
	v_mov_b64_e32 v[62:63], v[46:47]
	v_mov_b64_e32 v[0:1], v[32:33]
	v_mov_b64_e32 v[16:17], v[32:33]
	s_mov_b64 s[18:19], s[78:79]
	s_mov_b64 s[20:21], s[84:85]
	v_mov_b64_e32 v[60:61], v[44:45]
	v_mov_b64_e32 v[58:59], v[42:43]
	v_mov_b64_e32 v[56:57], v[40:41]
	v_mov_b64_e32 v[54:55], v[38:39]
	v_mov_b64_e32 v[52:53], v[36:37]
	v_mov_b64_e32 v[50:51], v[34:35]
	v_mov_b64_e32 v[48:49], v[32:33]
	v_mov_b64_e32 v[2:3], v[34:35]
	v_mov_b64_e32 v[4:5], v[36:37]
	v_mov_b64_e32 v[6:7], v[38:39]
	v_mov_b64_e32 v[8:9], v[40:41]
	v_mov_b64_e32 v[10:11], v[42:43]
	v_mov_b64_e32 v[12:13], v[44:45]
	v_mov_b64_e32 v[14:15], v[46:47]
	v_mov_b64_e32 v[18:19], v[34:35]
	v_mov_b64_e32 v[20:21], v[36:37]
	v_mov_b64_e32 v[22:23], v[38:39]
	v_mov_b64_e32 v[24:25], v[40:41]
	v_mov_b64_e32 v[26:27], v[42:43]
	v_mov_b64_e32 v[28:29], v[44:45]
	v_mov_b64_e32 v[30:31], v[46:47]
